# P2x RWKV sample iteration: the four token load groups no longer wait + convert one after the other (raw values in own registers, one wait + 20 conversions behind the last group)
# speedup vs baseline: 1.0019x; 1.0019x over previous
.LBB0_617:
	v_mov_b32_e32 v191, 0
	v_mov_b32_e32 v192, 0
	v_mov_b32_e32 v193, 0
	v_mov_b32_e32 v194, 0
	v_mov_b32_e32 v195, 0
	v_mov_b32_e32 v196, 0
	v_mov_b32_e32 v197, 0
	v_mov_b32_e32 v198, 0
	v_mov_b32_e32 v199, 0
	v_mov_b32_e32 v200, 0
	v_mov_b32_e32 v201, 0
	v_mov_b32_e32 v202, 0
	v_mov_b32_e32 v203, 0
	v_mov_b32_e32 v204, 0
	v_mov_b32_e32 v205, 0
	v_mov_b32_e32 v206, 0
	v_mov_b32_e32 v207, 0
	v_mov_b32_e32 v211, 0
	v_mov_b32_e32 v212, 0
	v_mov_b32_e32 v213, 0
	s_ashr_i32 s0, s43, 3
	s_ashr_i32 s1, s0, 31
	s_lshl_b64 s[2:3], s[0:1], 9
	s_and_b32 s82, s74, 0x1c0
	v_or_b32_e32 v0, s2, v54
	v_or_b32_e32 v16, s82, v158
	v_readlane_b32 s44, v250, 23
	v_mov_b32_e32 v23, s3
	v_or_b32_e32 v22, s82, v0
	v_lshlrev_b32_e32 v20, 2, v16
	v_readlane_b32 s45, v250, 24
	v_lshlrev_b64 v[0:1], 8, v[22:23]
	v_lshl_add_u64 v[0:1], v[58:59], 0, v[0:1]
	v_lshl_add_u64 v[16:17], s[44:45], 0, v[20:21]
	v_add_co_u32_e32 v16, vcc, 0x1000, v16
	global_load_dwordx4 v[12:15], v[0:1], off
	global_load_dwordx4 v[8:11], v[0:1], off offset:64
	global_load_dwordx4 v[4:7], v[0:1], off offset:128
	s_nop 0
	global_load_dwordx4 v[0:3], v[0:1], off offset:192
	v_readlane_b32 s56, v250, 35
	v_readlane_b32 s57, v250, 36
	v_readlane_b32 s58, v250, 37
	v_readlane_b32 s59, v250, 38
	v_addc_co_u32_e32 v17, vcc, 0, v17, vcc
	global_load_dword v47, v20, s[44:45]
	global_load_dword v45, v20, s[44:45] offset:2048
	global_load_dword v43, v20, s[56:57]
	s_nop 0
	global_load_dword v42, v20, s[58:59]
	global_load_dword v46, v[16:17], off
	v_readlane_b32 s44, v249, 60
	v_readlane_b32 s45, v249, 61
	s_and_b32 s1, s43, -8
	s_mov_b64 s[2:3], -1
	s_and_b64 vcc, exec, s[44:45]
	v_readlane_b32 s46, v250, 25
	v_readlane_b32 s47, v250, 26
	v_readlane_b32 s48, v250, 27
	v_readlane_b32 s49, v250, 28
	v_readlane_b32 s50, v250, 29
	v_readlane_b32 s51, v250, 30
	v_readlane_b32 s52, v250, 31
	v_readlane_b32 s53, v250, 32
	v_readlane_b32 s54, v250, 33
	v_readlane_b32 s55, v250, 34
	s_cbranch_vccz .LBB0_620
	s_andn2_b64 vcc, exec, s[72:73]
	s_cbranch_vccnz .LBB0_647
	s_add_i32 s2, s1, 0x4003
	s_mul_hi_i32 s3, s2, 0xe00
	s_mulk_i32 s2, 0xe00
	s_add_u32 s2, s60, s2
	s_addc_u32 s3, s61, s3
	s_lshl_b32 s44, s82, 1
	s_add_u32 s2, s2, s44
	s_addc_u32 s3, s3, 0
	global_load_ushort v16, v48, s[2:3]
	global_load_ushort v17, v48, s[2:3] offset:1024
	global_load_ushort v18, v48, s[2:3] offset:2048
	s_mov_b64 s[2:3], 0
	s_waitcnt vmcnt(2)
	v_lshlrev_b32_e32 v35, 16, v16
	s_waitcnt vmcnt(1)
	v_lshlrev_b32_e32 v33, 16, v17
	s_waitcnt vmcnt(0)
	v_lshlrev_b32_e32 v32, 16, v18

.LBB0_622:
	v_readlane_b32 s46, v248, 7
	v_readlane_b32 s47, v248, 8
	s_add_i32 s2, s1, 0x4000
	v_readlane_b32 s0, v249, 58
	s_lshl_b32 s78, s82, 1
	v_cndmask_b32_e64 v16, 0, 1, s[46:47]
	s_add_i32 s0, s2, s0
	v_cmp_ne_u32_e64 s[44:45], 1, v16
	s_andn2_b64 vcc, exec, s[46:47]
	v_lshl_add_u64 v[38:39], v[52:53], 0, s[78:79]
	s_cbranch_vccnz .LBB0_626
	s_ashr_i32 s1, s0, 31
	v_mad_i64_i32 v[16:17], s[54:55], s0, v41, v[38:39]
	s_lshl_b64 s[54:55], s[0:1], 9
	v_mov_b32_e32 v18, s82
	v_or3_b32 v19, s55, 0, 0
	v_or3_b32 v18, s54, v158, v18
	v_lshlrev_b64 v[18:19], 1, v[18:19]
	v_lshl_add_u64 v[24:25], s[66:67], 0, v[18:19]
	global_load_ushort v191, v[16:17], off
	global_load_ushort v192, v[16:17], off offset:2048
	global_load_ushort v193, v[16:17], off offset:1024
	v_lshl_add_u64 v[16:17], s[90:91], 0, v[18:19]
	global_load_ushort v194, v[24:25], off
	s_nop 0
	global_load_ushort v195, v[16:17], off
	s_and_b64 vcc, exec, s[44:45]
	s_cbranch_vccz .LBB0_627

.LBB0_627:
	s_or_b32 s54, s0, 1
	v_mad_i64_i32 v[16:17], s[68:69], s54, v41, v[38:39]
	s_ashr_i32 s55, s54, 31
	v_readlane_b32 s56, v250, 60
	v_readlane_b32 s64, v249, 4
	v_readlane_b32 s65, v249, 5
	v_readlane_b32 s66, v249, 6
	v_readlane_b32 s67, v249, 7
	v_readlane_b32 s68, v249, 8
	v_readlane_b32 s69, v249, 9
	s_lshl_b64 s[54:55], s[54:55], 9
	v_mov_b32_e32 v18, s82
	v_readlane_b32 s70, v249, 10
	v_readlane_b32 s71, v249, 11
	s_mov_b64 s[64:65], s[68:69]
	v_or3_b32 v19, s55, 0, 0
	v_or3_b32 v18, s54, v158, v18
	s_mov_b64 s[66:67], s[70:71]
	v_lshlrev_b64 v[18:19], 1, v[18:19]
	v_lshl_add_u64 v[24:25], s[66:67], 0, v[18:19]
	global_load_ushort v196, v[16:17], off
	global_load_ushort v197, v[16:17], off offset:2048
	global_load_ushort v198, v[16:17], off offset:1024
	v_lshl_add_u64 v[16:17], s[90:91], 0, v[18:19]
	global_load_ushort v199, v[24:25], off
	s_nop 0
	global_load_ushort v200, v[16:17], off
	v_readlane_b32 s57, v250, 61
	v_readlane_b32 s58, v250, 62
	v_readlane_b32 s59, v250, 63
	v_readlane_b32 s60, v249, 0
	v_readlane_b32 s61, v249, 1
	v_readlane_b32 s62, v249, 2
	v_readlane_b32 s63, v249, 3
	s_and_b64 vcc, exec, s[44:45]
	s_cbranch_vccnz .LBB0_625
.LBB0_628:
	s_or_b32 s54, s0, 2
	v_mad_i64_i32 v[16:17], s[68:69], s54, v41, v[38:39]
	s_ashr_i32 s55, s54, 31
	v_readlane_b32 s56, v250, 60
	v_readlane_b32 s64, v249, 4
	v_readlane_b32 s65, v249, 5
	v_readlane_b32 s66, v249, 6
	v_readlane_b32 s67, v249, 7
	v_readlane_b32 s68, v249, 8
	v_readlane_b32 s69, v249, 9
	s_lshl_b64 s[54:55], s[54:55], 9
	v_mov_b32_e32 v19, s82
	v_readlane_b32 s70, v249, 10
	v_readlane_b32 s71, v249, 11
	s_mov_b64 s[64:65], s[68:69]
	v_or3_b32 v25, s55, 0, 0
	v_or3_b32 v24, s54, v158, v19
	s_mov_b64 s[66:67], s[70:71]
	v_lshlrev_b64 v[24:25], 1, v[24:25]
	v_lshl_add_u64 v[86:87], s[66:67], 0, v[24:25]
	global_load_ushort v201, v[16:17], off
	global_load_ushort v202, v[16:17], off offset:2048
	global_load_ushort v203, v[16:17], off offset:1024
	v_lshl_add_u64 v[16:17], s[90:91], 0, v[24:25]
	global_load_ushort v204, v[86:87], off
	s_nop 0
	global_load_ushort v205, v[16:17], off
	v_readlane_b32 s57, v250, 61
	v_readlane_b32 s58, v250, 62
	v_readlane_b32 s59, v250, 63
	v_readlane_b32 s62, v249, 2
	v_readlane_b32 s63, v249, 3
	v_readlane_b32 s60, v249, 0
	v_readlane_b32 s61, v249, 1
.LBB0_629:
	v_readlane_b32 s60, v249, 16
	v_readlane_b32 s61, v249, 17
	v_mov_b32_e32 v64, 0
	s_and_b64 vcc, exec, s[44:45]
	v_mov_b32_e32 v16, 0
	v_mov_b32_e32 v70, 0
	v_mov_b32_e32 v19, 0
	v_mov_b32_e32 v17, 0
	v_mov_b32_e32 v20, 0
	s_cbranch_vccnz .LBB0_631
	s_or_b32 s0, s0, 3
	s_ashr_i32 s1, s0, 31
	v_mad_i64_i32 v[16:17], s[54:55], s0, v41, v[38:39]
	s_lshl_b64 s[0:1], s[0:1], 9
	v_mov_b32_e32 v19, s82
	v_or3_b32 v39, s1, 0, 0
	v_or3_b32 v38, s0, v158, v19
	v_lshlrev_b64 v[38:39], 1, v[38:39]
	v_lshl_add_u64 v[86:87], s[66:67], 0, v[38:39]
	global_load_ushort v206, v[16:17], off
	global_load_ushort v207, v[16:17], off offset:2048
	global_load_ushort v211, v[16:17], off offset:1024
	v_lshl_add_u64 v[16:17], s[90:91], 0, v[38:39]
	global_load_ushort v212, v[86:87], off
	s_nop 0
	global_load_ushort v213, v[16:17], off
.LBB0_631:
	s_waitcnt vmcnt(0)
	v_lshlrev_b32_e32 v29, 16, v191
	v_lshlrev_b32_e32 v30, 16, v192
	v_lshlrev_b32_e32 v31, 16, v193
	v_lshlrev_b32_e32 v37, 16, v194
	v_lshlrev_b32_e32 v36, 16, v195
	v_lshlrev_b32_e32 v18, 16, v196
	v_lshlrev_b32_e32 v26, 16, v197
	v_lshlrev_b32_e32 v27, 16, v198
	v_lshlrev_b32_e32 v51, 16, v199
	v_lshlrev_b32_e32 v34, 16, v200
	v_lshlrev_b32_e32 v49, 16, v201
	v_lshlrev_b32_e32 v24, 16, v202
	v_lshlrev_b32_e32 v25, 16, v203
	v_lshlrev_b32_e32 v66, 16, v204
	v_lshlrev_b32_e32 v28, 16, v205
	v_lshlrev_b32_e32 v19, 16, v206
	v_lshlrev_b32_e32 v20, 16, v207
	v_lshlrev_b32_e32 v17, 16, v211
	v_lshlrev_b32_e32 v70, 16, v212
	v_lshlrev_b32_e32 v16, 16, v213
	v_readlane_b32 s0, v249, 62
	s_and_b64 vcc, exec, s[44:45]
	s_nop 0
	v_add_u32_e32 v68, s0, v65
	ds_write_b32 v68, v37 offset:13824
	v_add_f32_e32 v37, 0, v37
	v_readlane_b32 s0, v248, 9
	v_add_f32_e32 v37, v37, v51
	v_add_f32_e32 v37, v37, v66
	v_add_u32_e32 v57, s0, v65
	v_readlane_b32 s0, v248, 10
	ds_write_b32 v57, v51 offset:13824
	v_add_f32_e32 v37, v37, v70
	v_add_u32_e32 v51, s0, v65
	v_readlane_b32 s0, v248, 11
	ds_write_b32 v51, v66 offset:13824
	ds_write_b32 v67, v37 offset:22016
	v_add_u32_e32 v39, s0, v65
	ds_write_b32 v39, v70 offset:13824
	s_waitcnt lgkmcnt(0)
	s_barrier
	ds_read2st64_b32 v[86:87], v65 offset0:86 offset1:87
	s_waitcnt lgkmcnt(0)
	v_add_f32_e32 v37, 0, v86
	v_cndmask_b32_e64 v37, v37, 0, s[84:85]
	v_cndmask_b32_e64 v38, 0, v87, s[40:41]
	v_add_f32_e32 v37, v37, v38
	ds_read_b32 v38, v65 offset:22528
	s_waitcnt lgkmcnt(0)
	v_cndmask_b32_e64 v38, 0, v38, s[38:39]
	v_add_f32_e32 v38, v37, v38
	s_cbranch_vccnz .LBB0_633
	ds_read_b32 v64, v68 offset:13824
	v_mul_f32_e32 v37, 0xbfb8aa3b, v38
	s_waitcnt vmcnt(0)
	v_pk_add_f32 v[32:33], v[32:33], v[30:31] neg_lo:[0,1] neg_hi:[0,1]
	v_exp_f32_e32 v86, v37
	v_fma_f32 v37, v45, v33, v31
	s_waitcnt lgkmcnt(0)
	v_add_f32_e32 v38, v38, v64
	v_mul_f32_e32 v64, v43, v37
	v_mul_f32_e32 v66, v64, v64
	v_mul_f32_e32 v33, 0xbfb8aa3b, v38
	v_exp_f32_e32 v33, v33
	v_mov_b32_dpp v66, v66 quad_perm:[1,0,3,2] row_mask:0xf bank_mask:0xf bound_ctrl:1
	v_fmac_f32_e32 v66, v64, v64
	v_sub_f32_e32 v35, v35, v29
	v_fma_f32 v87, v47, v35, v29
	v_add_f32_dpp v66, v66, v66 quad_perm:[2,3,0,1] row_mask:0xf bank_mask:0xf bound_ctrl:1
	v_fma_f32 v35, v46, v32, v30
	s_nop 0
	v_add_f32_dpp v66, v66, v66 row_ror:4 row_mask:0xf bank_mask:0xf bound_ctrl:1
	s_nop 1
	v_add_f32_dpp v66, v66, v66 row_ror:8 row_mask:0xf bank_mask:0xf bound_ctrl:1
	s_nop 0
	v_readlane_b32 s3, v66, 16
	v_readlane_b32 s51, v66, 48
	v_readlane_b32 s0, v66, 0
	v_readlane_b32 s1, v66, 32
	v_mov_b32_e32 v88, s3
	v_mov_b32_e32 v89, s51
	v_pk_add_f32 v[88:89], s[0:1], v[88:89]
	s_nop 0
	v_add_f32_e32 v66, v88, v89
	v_rsq_f32_e32 v68, v66
	v_mul_f32_e32 v66, 0x3fb8aa3b, v38
	v_exp_f32_e32 v66, v66
	v_min_f32_e32 v68, 0x5368d4a5, v68
	s_nop 0
	v_mul_f32_e32 v88, v64, v68
	v_xor_b32_e32 v32, 0x80000000, v88
	v_pk_mul_f32 v[32:33], v[86:87], v[32:33]
	s_nop 0
	v_cvt_pk_bf16_f32 v64, v32, v33
	v_add_f32_e32 v32, -1.0, v36
	v_fma_f32 v89, v42, v32, 1.0
	v_pk_mul_f32 v[32:33], v[36:37], v[88:89]
	v_lshrrev_b32_e32 v37, 16, v64
	v_pk_mul_f32 v[32:33], v[66:67], v[32:33] op_sel_hi:[0,1]
	v_cvt_pk_bf16_f32 v36, v32, v33
	v_bfe_u32 v32, v35, 16, 1
	v_add3_u32 v32, v35, v32, s81
	v_lshrrev_b32_e32 v66, 16, v36
	v_lshrrev_b32_e32 v68, 16, v32
	s_branch .LBB0_634
